# one static s_setprio 1 for waves 4-7 at kernel start (no per-segment flips)
# baseline (speedup 1.0000x reference)
; __device__ __forceinline__ int tid_of(int wave_id) { int t = wave_id * 64 + lane_id(); asm volatile("" : "+v"(t)); return t; }
; #define LAS __attribute__((address_space(3)))
; __device__ __forceinline__ float siluf_(float x) { return x * __builtin_amdgcn_rcpf(1.0f + __expf(-x)); }
; __device__ __forceinline__ void phase_mod(const Params& p, LAS unsigned char* lds, int vb, int nb) {
;     const int tid = tid_of(p.wave_id);
;     LAS float* sc = (LAS float*)lds;
;     LAS float* red = (LAS float*)(lds + 5 * 2048 * 4);
;     {
;         static_assert(D_MODEL == 4 * NTHREADS, "one f32x4 per thread and row");
;         f32x4 cv[5];
; #pragma unroll
;         for (int j = 0; j < 5; ++j) cv[j] = *(const f32x4*)((j < 4 ? p.c + j * D_MODEL : p.c_ctx) + 4 * tid);
; #pragma unroll
;         for (int j = 0; j < 5; ++j) { f32x4 o; o.x = siluf_(cv[j].x); o.y = siluf_(cv[j].y); o.z = siluf_(cv[j].z); o.w = siluf_(cv[j].w); *(LAS f32x4*)(sc + j * D_MODEL + 4 * tid) = o; } }
;     __syncthreads();
.LBB0_8:
	s_mov_b64 s[4:5], s[0:1]
	s_and_b32 s76, s3, 0xffffffc0
	s_cmp_ge_u32 s76, 0x100
	s_cbranch_scc0 .Lprio_done
	s_setprio 1
.Lprio_done:
	s_load_dwordx2 s[6:7], s[4:5], 0x8
	s_load_dwordx4 s[16:19], s[4:5], 0x18
	s_load_dwordx2 s[24:25], s[4:5], 0x28
	s_load_dwordx4 s[12:15], s[4:5], 0x38
	s_load_dwordx2 s[22:23], s[4:5], 0x48
	s_load_dwordx2 s[20:21], s[4:5], 0xb8
	v_mbcnt_lo_u32_b32 v0, -1, 0
	v_mbcnt_hi_u32_b32 v0, -1, v0
	s_movk_i32 s38, 0x2000
	v_add_u32_e32 v24, s76, v0
	s_movk_i32 s4, 0x4000
	v_lshlrev_b32_e32 v0, 2, v24
	v_ashrrev_i32_e32 v1, 31, v0
	v_lshlrev_b64 v[18:19], 2, v[0:1]
	s_waitcnt lgkmcnt(0)
	v_lshl_add_u64 v[14:15], s[6:7], 0, v[18:19]
	v_add_co_u32_e32 v6, vcc, s38, v14
	global_load_dwordx4 v[2:5], v[14:15], off
	s_nop 0
	v_addc_co_u32_e32 v7, vcc, 0, v15, vcc
	v_add_co_u32_e32 v10, vcc, s4, v14
	s_movk_i32 s4, 0x6000
	s_nop 0
	v_addc_co_u32_e32 v11, vcc, 0, v15, vcc
	global_load_dwordx4 v[6:9], v[6:7], off
	v_add_co_u32_e32 v14, vcc, s4, v14
	global_load_dwordx4 v[10:13], v[10:11], off
	s_nop 0
	v_addc_co_u32_e32 v15, vcc, 0, v15, vcc
	global_load_dwordx4 v[14:17], v[14:15], off
	v_lshl_add_u64 v[18:19], s[16:17], 0, v[18:19]
	global_load_dwordx4 v[18:21], v[18:19], off
	v_lshl_add_u32 v1, v24, 4, 0
	s_cmpk_gt_i32 s74, 0xbf
	s_waitcnt vmcnt(4)
	v_mul_f32_e32 v22, 0xbfb8aa3b, v2
	v_mul_f32_e32 v23, 0xbfb8aa3b, v3
	v_mul_f32_e32 v25, 0xbfb8aa3b, v4
	v_mul_f32_e32 v26, 0xbfb8aa3b, v5
	v_exp_f32_e32 v22, v22
	v_exp_f32_e32 v23, v23
	v_exp_f32_e32 v25, v25
	v_exp_f32_e32 v26, v26
	s_waitcnt vmcnt(3)
	v_mul_f32_e32 v27, 0xbfb8aa3b, v6
	v_mul_f32_e32 v28, 0xbfb8aa3b, v7
	v_mul_f32_e32 v29, 0xbfb8aa3b, v8
	v_mul_f32_e32 v30, 0xbfb8aa3b, v9
	s_waitcnt vmcnt(2)
	v_mul_f32_e32 v31, 0xbfb8aa3b, v10
	v_mul_f32_e32 v32, 0xbfb8aa3b, v11
	v_mul_f32_e32 v33, 0xbfb8aa3b, v12
	v_mul_f32_e32 v34, 0xbfb8aa3b, v13
	v_exp_f32_e32 v38, v27
	v_exp_f32_e32 v28, v28
	v_exp_f32_e32 v29, v29
	v_exp_f32_e32 v30, v30
	s_waitcnt vmcnt(1)
	v_mul_f32_e32 v35, 0xbfb8aa3b, v14
	v_exp_f32_e32 v31, v31
	v_exp_f32_e32 v32, v32
	v_exp_f32_e32 v33, v33
	v_exp_f32_e32 v34, v34
	v_exp_f32_e32 v35, v35
	v_mul_f32_e32 v36, 0xbfb8aa3b, v16
	v_add_f32_e32 v22, 1.0, v22
	v_add_f32_e32 v23, 1.0, v23
	v_add_f32_e32 v25, 1.0, v25
	v_add_f32_e32 v27, 1.0, v26
	v_exp_f32_e32 v39, v36
	v_rcp_f32_e32 v22, v22
	v_rcp_f32_e32 v23, v23
	v_rcp_f32_e32 v26, v25
	v_rcp_f32_e32 v27, v27
	v_add_f32_e32 v25, 1.0, v38
	v_add_f32_e32 v36, 1.0, v28
	v_add_f32_e32 v38, 1.0, v29
	v_add_f32_e32 v40, 1.0, v30
	v_add_f32_e32 v41, 1.0, v31
	v_add_f32_e32 v42, 1.0, v32
	v_add_f32_e32 v43, 1.0, v33
	v_add_f32_e32 v44, 1.0, v34
	v_rcp_f32_e32 v28, v25
	v_rcp_f32_e32 v29, v36
	v_rcp_f32_e32 v30, v38
	v_rcp_f32_e32 v31, v40
	v_add_f32_e32 v45, 1.0, v35
	v_rcp_f32_e32 v32, v41
	v_rcp_f32_e32 v33, v42
	v_rcp_f32_e32 v34, v43
	v_rcp_f32_e32 v35, v44
	v_pk_mul_f32 v[4:5], v[4:5], v[26:27]
	v_pk_mul_f32 v[2:3], v[2:3], v[22:23]
	ds_write_b128 v1, v[2:5]
	v_pk_mul_f32 v[4:5], v[8:9], v[30:31]
	v_pk_mul_f32 v[2:3], v[6:7], v[28:29]
	v_pk_mul_f32 v[8:9], v[12:13], v[34:35]
	v_pk_mul_f32 v[6:7], v[10:11], v[32:33]
	ds_write_b128 v1, v[2:5] offset:8192
	ds_write_b128 v1, v[6:9] offset:16384
	v_mul_f32_e32 v2, 0xbfb8aa3b, v17
	v_exp_f32_e32 v3, v2
	v_mul_f32_e32 v37, 0xbfb8aa3b, v15
	v_exp_f32_e32 v4, v37
	v_add_f32_e32 v2, 1.0, v39
	v_add_f32_e32 v3, 1.0, v3
	s_waitcnt vmcnt(0)
	v_mul_f32_e32 v5, 0xbfb8aa3b, v18
	v_rcp_f32_e32 v2, v2
	v_rcp_f32_e32 v3, v3
	v_exp_f32_e32 v6, v5
	v_add_f32_e32 v4, 1.0, v4
	v_rcp_f32_e32 v37, v4
	v_pk_mul_f32 v[4:5], v[16:17], v[2:3]
	v_add_f32_e32 v2, 1.0, v6
	v_mul_f32_e32 v3, 0xbfb8aa3b, v20
	v_rcp_f32_e32 v6, v2
	v_mul_f32_e32 v2, 0xbfb8aa3b, v19
	v_exp_f32_e32 v3, v3
	v_mul_f32_e32 v7, 0xbfb8aa3b, v21
	v_exp_f32_e32 v2, v2
	v_exp_f32_e32 v7, v7
	v_add_f32_e32 v3, 1.0, v3
	v_rcp_f32_e32 v36, v45
	v_add_f32_e32 v2, 1.0, v2
	v_rcp_f32_e32 v8, v3
	v_add_f32_e32 v3, 1.0, v7
	v_rcp_f32_e32 v9, v3
	v_rcp_f32_e32 v7, v2
	v_pk_mul_f32 v[2:3], v[14:15], v[36:37]
	ds_write_b128 v1, v[2:5] offset:24576
	v_pk_mul_f32 v[4:5], v[20:21], v[8:9]
	v_pk_mul_f32 v[2:3], v[18:19], v[6:7]
	ds_write_b128 v1, v[2:5] offset:32768
	s_waitcnt lgkmcnt(0)
	s_barrier
	s_cbranch_scc0 .LBB0_11
	s_add_i32 s4, s33, -1
	s_cmp_lg_u32 s74, s4
	s_cbranch_scc0 .LBB0_31
